# nt (streaming) cache hint on the once-read f32 weight loads of the weight-conversion loops (P0 and the idle-WG conversion in P1)
# speedup vs baseline: 1.0112x; 1.0112x over previous
; DI void tr_load(const TrItem& t, f32x4 (&v)[8], int lane) {
;     if (t.src < 0) return;
;     const float* wp = t.W + (size_t)(t.k0 + (lane >> 3)) * t.srcN + t.src + (lane & 7) * 4;
; #pragma unroll
;     for (int i = 0; i < 8; ++i) v[i] = *(const f32x4*)(wp + (size_t)(8 * i) * t.srcN);
; }
.LBB0_70:
	s_lshl_b32 s6, s15, 6
	s_cmp_gt_i32 s4, -1
	s_cselect_b64 s[18:19], -1, 0
	s_cmp_lt_i32 s4, 0
	s_cbranch_scc1 .LBB0_72
	s_waitcnt vmcnt(7)
	v_or_b32_e32 v10, s6, v65
	s_waitcnt lgkmcnt(0)
	v_mov_b64_e32 v[8:9], s[12:13]
	v_mad_i64_i32 v[8:9], s[20:21], v10, s3, v[8:9]
	v_lshl_add_u64 v[8:9], s[4:5], 2, v[8:9]
	v_lshlrev_b32_e32 v66, 2, v64
	s_waitcnt vmcnt(1)
	v_lshl_add_u64 v[48:49], v[8:9], 0, v[66:67]
	v_add_co_u32_e32 v20, vcc, 0x5a000, v48
	s_nop 1
	v_addc_co_u32_e32 v21, vcc, 0, v49, vcc
	v_add_co_u32_e32 v28, vcc, 0xb5000, v48
	global_load_dwordx4 v[8:11], v[48:49], off nt
	global_load_dwordx4 v[16:19], v[20:21], off offset:2048 nt
	v_addc_co_u32_e32 v29, vcc, 0, v49, vcc
	v_add_co_u32_e32 v30, vcc, 0x10f000, v48
	s_nop 1
	v_addc_co_u32_e32 v31, vcc, 0, v49, vcc
	v_add_co_u32_e32 v50, vcc, 0x16a000, v48
	global_load_dwordx4 v[20:23], v[28:29], off nt
	global_load_dwordx4 v[24:27], v[30:31], off offset:2048 nt
	v_addc_co_u32_e32 v51, vcc, 0, v49, vcc
	s_waitcnt vmcnt(4)
	v_add_co_u32_e32 v52, vcc, 0x1c4000, v48
	s_nop 1
	v_addc_co_u32_e32 v53, vcc, 0, v49, vcc
	v_add_co_u32_e32 v70, vcc, 0x21f000, v48
	global_load_dwordx4 v[28:31], v[50:51], off nt
	global_load_dwordx4 v[36:39], v[52:53], off offset:2048 nt
	v_addc_co_u32_e32 v71, vcc, 0, v49, vcc
	v_add_co_u32_e32 v72, vcc, 0x279000, v48
	s_nop 1
	v_addc_co_u32_e32 v73, vcc, 0, v49, vcc
	global_load_dwordx4 v[48:51], v[70:71], off nt
	global_load_dwordx4 v[52:55], v[72:73], off offset:2048 nt

; DI void tr_load(const TrItem& t, f32x4 (&v)[8], int lane) {
;     if (t.src < 0) return;
;     const float* wp = t.W + (size_t)(t.k0 + (lane >> 3)) * t.srcN + t.src + (lane & 7) * 4;
; #pragma unroll
;     for (int i = 0; i < 8; ++i) v[i] = *(const f32x4*)(wp + (size_t)(8 * i) * t.srcN);
; }
.LBB0_82:
	s_lshl_b32 s16, s4, 6
	s_cmp_lt_i32 s14, 0
	s_cbranch_scc1 .LBB0_84
	s_waitcnt vmcnt(7)
	v_or_b32_e32 v2, s16, v65
	s_waitcnt lgkmcnt(0)
	v_mov_b64_e32 v[0:1], s[12:13]
	v_mad_i64_i32 v[0:1], s[22:23], v2, s3, v[0:1]
	s_mov_b32 s15, s5
	v_lshl_add_u64 v[0:1], s[14:15], 2, v[0:1]
	v_lshlrev_b32_e32 v66, 2, v64
	s_waitcnt vmcnt(1)
	v_lshl_add_u64 v[56:57], v[0:1], 0, v[66:67]
	v_add_co_u32_e32 v12, vcc, 0x5a000, v56
	s_nop 1
	v_addc_co_u32_e32 v13, vcc, 0, v57, vcc
	v_add_co_u32_e32 v40, vcc, 0xb5000, v56
	global_load_dwordx4 v[0:3], v[56:57], off nt
	global_load_dwordx4 v[4:7], v[12:13], off offset:2048 nt
	v_addc_co_u32_e32 v41, vcc, 0, v57, vcc
	v_add_co_u32_e32 v42, vcc, 0x10f000, v56
	s_nop 1
	v_addc_co_u32_e32 v43, vcc, 0, v57, vcc
	v_add_co_u32_e32 v58, vcc, 0x16a000, v56
	global_load_dwordx4 v[12:15], v[40:41], off nt
	global_load_dwordx4 v[32:35], v[42:43], off offset:2048 nt
	v_addc_co_u32_e32 v59, vcc, 0, v57, vcc
	s_waitcnt vmcnt(4)
	v_add_co_u32_e32 v60, vcc, 0x1c4000, v56
	s_nop 1
	v_addc_co_u32_e32 v61, vcc, 0, v57, vcc
	v_add_co_u32_e32 v70, vcc, 0x21f000, v56
	global_load_dwordx4 v[40:43], v[58:59], off nt
	global_load_dwordx4 v[44:47], v[60:61], off offset:2048 nt
	v_addc_co_u32_e32 v71, vcc, 0, v57, vcc
	v_add_co_u32_e32 v72, vcc, 0x279000, v56
	s_nop 1
	v_addc_co_u32_e32 v73, vcc, 0, v57, vcc
	global_load_dwordx4 v[56:59], v[70:71], off nt
	global_load_dwordx4 v[60:63], v[72:73], off offset:2048 nt

; DI void tr_load(const TrItem& t, f32x4 (&v)[8], int lane) {
;     if (t.src < 0) return;
;     const float* wp = t.W + (size_t)(t.k0 + (lane >> 3)) * t.srcN + t.src + (lane & 7) * 4;
; #pragma unroll
;     for (int i = 0; i < 8; ++i) v[i] = *(const f32x4*)(wp + (size_t)(8 * i) * t.srcN);
; }
.LBB0_258:
	s_lshl_b32 s10, s77, 6
	s_cmp_gt_i32 s8, -1
	s_cselect_b64 s[4:5], -1, 0
	s_cmp_lt_i32 s8, 0
	v_or_b32_e32 v70, s10, v67
	s_cbranch_scc1 .LBB0_260
	s_ashr_i32 s11, s10, 31
	v_mul_lo_u32 v0, s15, v70
	s_mul_i32 s11, s14, s11
	s_waitcnt vmcnt(7)
	v_mad_u64_u32 v[2:3], s[80:81], s14, v70, 0
	v_add3_u32 v3, v3, s11, v0
	s_waitcnt lgkmcnt(0)
	v_lshl_add_u64 v[2:3], v[2:3], 2, s[18:19]
	v_lshl_add_u64 v[2:3], s[8:9], 2, v[2:3]
	v_lshlrev_b32_e32 v0, 2, v66
	v_lshl_add_u64 v[2:3], v[2:3], 0, v[0:1]
	s_lshl_b64 s[14:15], s[14:15], 5
	s_waitcnt vmcnt(5)
	v_lshl_add_u64 v[10:11], v[2:3], 0, s[14:15]
	global_load_dwordx4 v[2:5], v[2:3], off nt
	s_nop 0
	global_load_dwordx4 v[6:9], v[10:11], off nt
	v_lshl_add_u64 v[10:11], v[10:11], 0, s[14:15]
	s_waitcnt vmcnt(5)
	v_lshl_add_u64 v[18:19], v[10:11], 0, s[14:15]
	global_load_dwordx4 v[10:13], v[10:11], off nt
	s_nop 0
	global_load_dwordx4 v[14:17], v[18:19], off nt
	v_lshl_add_u64 v[18:19], v[18:19], 0, s[14:15]
	s_waitcnt vmcnt(5)
	v_lshl_add_u64 v[26:27], v[18:19], 0, s[14:15]
	global_load_dwordx4 v[18:21], v[18:19], off nt
	s_nop 0
	global_load_dwordx4 v[22:25], v[26:27], off nt
	v_lshl_add_u64 v[26:27], v[26:27], 0, s[14:15]
	s_waitcnt vmcnt(6)
	v_lshl_add_u64 v[30:31], v[26:27], 0, s[14:15]
	global_load_dwordx4 v[26:29], v[26:27], off nt
	s_nop 0
	global_load_dwordx4 v[30:33], v[30:31], off nt

; DI void tr_load(const TrItem& t, f32x4 (&v)[8], int lane) {
;     if (t.src < 0) return;
;     const float* wp = t.W + (size_t)(t.k0 + (lane >> 3)) * t.srcN + t.src + (lane & 7) * 4;
; #pragma unroll
;     for (int i = 0; i < 8; ++i) v[i] = *(const f32x4*)(wp + (size_t)(8 * i) * t.srcN);
; }
.LBB0_294:
	s_lshl_b32 s76, s8, 6
	s_cmp_lt_i32 s70, 0
	s_cbranch_scc1 .LBB0_296
	v_or_b32_e32 v0, s76, v67
	s_ashr_i32 s8, s76, 31
	s_waitcnt vmcnt(7)
	v_mul_lo_u32 v36, s81, v0
	s_mul_i32 s8, s80, s8
	v_mad_u64_u32 v[34:35], s[88:89], s80, v0, 0
	v_add3_u32 v35, v35, s8, v36
	s_waitcnt lgkmcnt(0)
	v_lshl_add_u64 v[34:35], v[34:35], 2, s[14:15]
	s_mov_b32 s71, s9
	v_lshl_add_u64 v[34:35], s[70:71], 2, v[34:35]
	v_lshlrev_b32_e32 v0, 2, v66
	v_lshl_add_u64 v[34:35], v[34:35], 0, v[0:1]
	s_lshl_b64 s[14:15], s[80:81], 5
	s_waitcnt vmcnt(5)
	v_lshl_add_u64 v[42:43], v[34:35], 0, s[14:15]
	global_load_dwordx4 v[34:37], v[34:35], off nt
	s_nop 0
	global_load_dwordx4 v[38:41], v[42:43], off nt
	v_lshl_add_u64 v[42:43], v[42:43], 0, s[14:15]
	s_waitcnt vmcnt(5)
	v_lshl_add_u64 v[50:51], v[42:43], 0, s[14:15]
	global_load_dwordx4 v[42:45], v[42:43], off nt
	s_nop 0
	global_load_dwordx4 v[46:49], v[50:51], off nt
	v_lshl_add_u64 v[50:51], v[50:51], 0, s[14:15]
	s_waitcnt vmcnt(5)
	v_lshl_add_u64 v[58:59], v[50:51], 0, s[14:15]
	global_load_dwordx4 v[50:53], v[50:51], off nt
	s_nop 0
	global_load_dwordx4 v[54:57], v[58:59], off nt
	v_lshl_add_u64 v[58:59], v[58:59], 0, s[14:15]
	s_waitcnt vmcnt(6)
	v_lshl_add_u64 v[62:63], v[58:59], 0, s[14:15]
	global_load_dwordx4 v[58:61], v[58:59], off nt
	s_nop 0
	global_load_dwordx4 v[62:65], v[62:63], off nt

; DI void tr_load(const TrItem& t, f32x4 (&v)[8], int lane) {
;     if (t.src < 0) return;
;     const float* wp = t.W + (size_t)(t.k0 + (lane >> 3)) * t.srcN + t.src + (lane & 7) * 4;
; #pragma unroll
;     for (int i = 0; i < 8; ++i) v[i] = *(const f32x4*)(wp + (size_t)(8 * i) * t.srcN);
; }
.LBB0_392:
	s_lshl_b32 s10, s75, 6
	s_cmp_gt_i32 s8, -1
	s_cselect_b64 s[4:5], -1, 0
	s_cmp_lt_i32 s8, 0
	v_or_b32_e32 v70, s10, v67
	s_cbranch_scc1 .LBB0_394
	s_ashr_i32 s11, s10, 31
	v_mul_lo_u32 v0, s15, v70
	s_mul_i32 s11, s14, s11
	s_waitcnt vmcnt(7)
	v_mad_u64_u32 v[2:3], s[78:79], s14, v70, 0
	v_add3_u32 v3, v3, s11, v0
	s_waitcnt lgkmcnt(0)
	v_lshl_add_u64 v[2:3], v[2:3], 2, s[18:19]
	v_lshl_add_u64 v[2:3], s[8:9], 2, v[2:3]
	v_lshlrev_b32_e32 v0, 2, v66
	v_lshl_add_u64 v[2:3], v[2:3], 0, v[0:1]
	s_lshl_b64 s[14:15], s[14:15], 5
	s_waitcnt vmcnt(5)
	v_lshl_add_u64 v[10:11], v[2:3], 0, s[14:15]
	global_load_dwordx4 v[2:5], v[2:3], off nt
	s_nop 0
	global_load_dwordx4 v[6:9], v[10:11], off nt
	v_lshl_add_u64 v[10:11], v[10:11], 0, s[14:15]
	s_waitcnt vmcnt(5)
	v_lshl_add_u64 v[18:19], v[10:11], 0, s[14:15]
	global_load_dwordx4 v[10:13], v[10:11], off nt
	s_nop 0
	global_load_dwordx4 v[14:17], v[18:19], off nt
	v_lshl_add_u64 v[18:19], v[18:19], 0, s[14:15]
	s_waitcnt vmcnt(5)
	v_lshl_add_u64 v[26:27], v[18:19], 0, s[14:15]
	global_load_dwordx4 v[18:21], v[18:19], off nt
	s_nop 0
	global_load_dwordx4 v[22:25], v[26:27], off nt
	v_lshl_add_u64 v[26:27], v[26:27], 0, s[14:15]
	s_waitcnt vmcnt(6)
	v_lshl_add_u64 v[30:31], v[26:27], 0, s[14:15]
	global_load_dwordx4 v[26:29], v[26:27], off nt
	s_nop 0
	global_load_dwordx4 v[30:33], v[30:31], off nt

; DI void tr_load(const TrItem& t, f32x4 (&v)[8], int lane) {
;     if (t.src < 0) return;
;     const float* wp = t.W + (size_t)(t.k0 + (lane >> 3)) * t.srcN + t.src + (lane & 7) * 4;
; #pragma unroll
;     for (int i = 0; i < 8; ++i) v[i] = *(const f32x4*)(wp + (size_t)(8 * i) * t.srcN);
; }
.LBB0_428:
	s_lshl_b32 s74, s8, 6
	s_cmp_lt_i32 s68, 0
	s_cbranch_scc1 .LBB0_430
	v_or_b32_e32 v0, s74, v67
	s_ashr_i32 s8, s74, 31
	s_waitcnt vmcnt(7)
	v_mul_lo_u32 v36, s79, v0
	s_mul_i32 s8, s78, s8
	v_mad_u64_u32 v[34:35], s[86:87], s78, v0, 0
	v_add3_u32 v35, v35, s8, v36
	s_waitcnt lgkmcnt(0)
	v_lshl_add_u64 v[34:35], v[34:35], 2, s[14:15]
	s_mov_b32 s69, s9
	v_lshl_add_u64 v[34:35], s[68:69], 2, v[34:35]
	v_lshlrev_b32_e32 v0, 2, v66
	v_lshl_add_u64 v[34:35], v[34:35], 0, v[0:1]
	s_lshl_b64 s[14:15], s[78:79], 5
	s_waitcnt vmcnt(5)
	v_lshl_add_u64 v[42:43], v[34:35], 0, s[14:15]
	global_load_dwordx4 v[34:37], v[34:35], off nt
	s_nop 0
	global_load_dwordx4 v[38:41], v[42:43], off nt
	v_lshl_add_u64 v[42:43], v[42:43], 0, s[14:15]
	s_waitcnt vmcnt(5)
	v_lshl_add_u64 v[50:51], v[42:43], 0, s[14:15]
	global_load_dwordx4 v[42:45], v[42:43], off nt
	s_nop 0
	global_load_dwordx4 v[46:49], v[50:51], off nt
	v_lshl_add_u64 v[50:51], v[50:51], 0, s[14:15]
	s_waitcnt vmcnt(5)
	v_lshl_add_u64 v[58:59], v[50:51], 0, s[14:15]
	global_load_dwordx4 v[50:53], v[50:51], off nt
	s_nop 0
	global_load_dwordx4 v[54:57], v[58:59], off nt
	v_lshl_add_u64 v[58:59], v[58:59], 0, s[14:15]
	s_waitcnt vmcnt(6)
	v_lshl_add_u64 v[62:63], v[58:59], 0, s[14:15]
	global_load_dwordx4 v[58:61], v[58:59], off nt
	s_nop 0
	global_load_dwordx4 v[62:65], v[62:63], off nt
